# as previous plus a 64-cycle stagger of waves 4-7 after each step barrier
# baseline (speedup 1.0000x reference)
; #define SBAR() __builtin_amdgcn_sched_barrier(0)
; __device__ __forceinline__ void finishSM(f32x16& p0, f32x16& p1, float alpha, float& l_reg, bf16x8& pa0, bf16x8& pa1, bf16x8& pa2, bf16x8& pa3) {
;   for (int r = 0; r < 16; ++r) p1[r] = __builtin_amdgcn_exp2f(p1[r]);
;   float ps = 0; for (int r = 0; r < 16; ++r) ps += p0[r]; for (int r = 0; r < 16; ++r) ps += p1[r];
;   { auto rr = __builtin_amdgcn_permlane32_swap(__float_as_uint(ps), __float_as_uint(ps), false, false);
;     ps = __uint_as_float(rr[0]) + __uint_as_float(rr[1]); }
;   l_reg = l_reg * alpha + ps;
;     ...
;   PK4(p0, 0, pa0); PK4(p0, 8, pa1); PK4(p1, 0, pa2); PK4(p1, 8, pa3);
;     ...
; }
; __device__ __forceinline__ void kload(bf16x8 (&kf)[8], const char* Ks, int r32, int hi, int sb) {
; #pragma unroll
;   for (int d0 = 0; d0 < 4; ++d0) { const int cb = sb + (d0 * 16 + hi * 8) * 2;
;     kf[2 * d0] = *reinterpret_cast<const bf16x8*>(Ks + KSWZ(r32, cb)); kf[2 * d0 + 1] = *reinterpret_cast<const bf16x8*>(Ks + KSWZ(32 + r32, cb)); }
; }
; __device__ __forceinline__ void kmma(f32x16& p0, f32x16& p1, const bf16x8 (&kf)[8], const bf16x8* qr) {
;   asm volatile("s_waitcnt lgkmcnt(0)" ::: "memory"); SBAR();
;   p0 = f32x16{}; p1 = f32x16{};
; #pragma unroll
;   for (int d0 = 0; d0 < 4; ++d0) { p0 = __builtin_amdgcn_mfma_f32_32x32x16_bf16(kf[2 * d0], qr[d0], p0, 0, 0, 0); p1 = __builtin_amdgcn_mfma_f32_32x32x16_bf16(kf[2 * d0 + 1], qr[d0], p1, 0, 0, 0); }
; }
; __device__ __forceinline__ void qkt(f32x16& p0, f32x16& p1, const char* Ks, const bf16x8* qr, int r32, int hi, int sb) {
;   bf16x8 kf[8]; kload(kf, Ks, r32, hi, sb); SBAR(); kmma(p0, p1, kf, qr);
.LBB0_774:
	s_waitcnt vmcnt(4)
	s_barrier
	v_readfirstlane_b32 s44, v0
	s_cmpk_lt_u32 s44, 0x100
	s_cbranch_scc1 .Lmy_ns1
	s_sleep 1
.Lmy_ns1:
	ds_read_b128 v[66:69], v245
	ds_read_b128 v[70:73], v245 offset:8192
	ds_read_b128 v[98:101], v246
	ds_read_b128 v[102:105], v246 offset:8192
	ds_read_b128 v[106:109], v247
	ds_read_b128 v[110:113], v247 offset:8192
	ds_read_b128 v[134:137], v255
	ds_read_b128 v[174:177], v255 offset:8192
	v_exp_f32_e32 v210, v82
	v_exp_f32_e32 v211, v83
	v_exp_f32_e32 v212, v84
	v_exp_f32_e32 v213, v85
	v_exp_f32_e32 v214, v86
	v_exp_f32_e32 v215, v87
	v_add_f32_e32 v216, 0, v192
	v_add_f32_e32 v216, v193, v216
	v_add_f32_e32 v216, v194, v216
	v_add_f32_e32 v216, v195, v216
	v_exp_f32_e32 v149, v149
	v_exp_f32_e32 v150, v150
	v_exp_f32_e32 v151, v151
	v_exp_f32_e32 v186, v186
	v_exp_f32_e32 v187, v187
	v_exp_f32_e32 v188, v188
	s_waitcnt lgkmcnt(7)
	v_mfma_f32_32x32x16_bf16 v[82:97], v[66:69], v[126:129], 0
	v_exp_f32_e32 v189, v189
	s_and_b32 s46, s13, 0xc000
	v_exp_f32_e32 v208, v208
	v_add_u32_e32 v244, s46, v164
	v_exp_f32_e32 v209, v209
	ds_read_b64_tr_b16 v[228:229], v244 offset:0
	v_exp_f32_e32 v148, v148
	ds_read_b64_tr_b16 v[230:231], v244 offset:0x800
	ds_read_b64_tr_b16 v[232:233], v244 offset:0x1000
	s_waitcnt lgkmcnt(9)
	v_mfma_f32_32x32x16_bf16 v[66:81], v[70:73], v[126:129], 0
	v_add_f32_e32 v255, v196, v216
	ds_read_b64_tr_b16 v[234:235], v244 offset:0x1800
	v_add_f32_e32 v255, v197, v255
	ds_read_b64_tr_b16 v[236:237], v244 offset:0x2000
	v_add_f32_e32 v255, v198, v255
	ds_read_b64_tr_b16 v[238:239], v244 offset:0x2800
	v_add_f32_e32 v255, v199, v255
	ds_read_b64_tr_b16 v[240:241], v244 offset:0x3000
	v_add_f32_e32 v255, v200, v255
	ds_read_b64_tr_b16 v[242:243], v244 offset:0x3800
	s_waitcnt lgkmcnt(13)
	v_mfma_f32_32x32x16_bf16 v[82:97], v[98:101], v[122:125], v[82:97]
	v_add_f32_e32 v255, v201, v255
	s_add_i32 s46, s12, 3
	v_add_f32_e32 v255, v202, v255
	s_cmpk_lt_u32 s12, 0x7d
	v_add_f32_e32 v255, v203, v255
	s_cselect_b64 s[42:43], -1, 0
	v_add_f32_e32 v255, v204, v255
	s_and_b64 s[44:45], s[42:43], exec
	s_cselect_b32 s44, 0, 0xffffff80
	s_waitcnt lgkmcnt(12)
	v_mfma_f32_32x32x16_bf16 v[66:81], v[102:105], v[122:125], v[66:81]
	v_add_f32_e32 v255, v205, v255
	s_add_i32 s58, s46, s44
	v_add_f32_e32 v255, v206, v255
	s_and_b64 s[42:43], s[42:43], exec
	v_add_f32_e32 v255, v207, v255
	s_cselect_b32 s43, s9, s30
	v_add_f32_e32 v255, v210, v255
	s_cselect_b32 s42, s8, s26
	v_add_f32_e32 v255, v211, v255
	s_lshl_b64 s[44:45], s[58:59], 17
	s_waitcnt lgkmcnt(11)
	v_mfma_f32_32x32x16_bf16 v[82:97], v[106:109], v[118:121], v[82:97]
	v_add_f32_e32 v255, v212, v255
	s_lshl_b64 s[42:43], s[42:43], 11
	v_add_f32_e32 v255, v213, v255
	s_add_u32 s44, s44, s42
	v_add_f32_e32 v255, v214, v255
	s_addc_u32 s45, s45, s43
	v_add_f32_e32 v255, v215, v255
	s_add_u32 s42, s20, s44
	s_addc_u32 s43, s21, s45
	s_waitcnt lgkmcnt(10)
	v_mfma_f32_32x32x16_bf16 v[66:81], v[110:113], v[118:121], v[66:81]
	v_add_f32_e32 v255, v149, v255
	s_add_u32 s44, s22, s44
	v_add_f32_e32 v255, v150, v255
	s_mul_i32 s47, s46, 0xab
	v_add_f32_e32 v255, v151, v255
	s_addc_u32 s45, s23, s45
	v_add_f32_e32 v255, v186, v255
	s_bfe_u32 s47, s47, 0x70009
	v_add_f32_e32 v255, v187, v255
	s_mul_i32 s47, s47, 3
	s_waitcnt lgkmcnt(9)
	v_mfma_f32_32x32x16_bf16 v[82:97], v[134:137], v[114:117], v[82:97]
	v_add_f32_e32 v255, v188, v255
	s_sub_i32 s46, s46, s47
	v_add_f32_e32 v255, v189, v255
	s_and_b32 s46, s46, 0xff
	v_add_f32_e32 v255, v208, v255
	s_lshl_b32 s46, s46, 14
	s_mov_b32 s101, s46
	v_add_f32_e32 v255, v209, v255
	s_add_i32 s46, s46, s27
	v_add_f32_e32 v99, v148, v255
	s_and_b32 s47, s36, 0xc000
	s_add_i32 s47, s47, s31
	s_cmpk_gt_u32 s12, 0x80
	s_cselect_b64 s[10:11], -1, 0
	s_and_b64 vcc, exec, s[10:11]
	s_cbranch_vccnz .LBB0_776
	v_lshl_add_u64 v[246:247], s[42:43], 0, v[146:147]
	s_mov_b32 m0, s46
	s_nop 0
	global_load_lds_dwordx4 v[246:247], off
	v_lshl_add_u64 v[246:247], s[44:45], 0, v[142:143]
	s_mov_b32 m0, s47
	s_nop 0
	global_load_lds_dwordx4 v[246:247], off
	v_lshl_add_u64 v[246:247], s[42:43], 0, v[144:145]
	s_add_i32 m0, s46, 0x2000
	s_nop 0
	global_load_lds_dwordx4 v[246:247], off
	v_lshl_add_u64 v[246:247], s[44:45], 0, v[154:155]
	s_add_i32 m0, s47, 0x2000
	s_nop 0
	global_load_lds_dwordx4 v[246:247], off

; #define SBAR() __builtin_amdgcn_sched_barrier(0)
; #define TILE_BAR(n) do { asm volatile("s_waitcnt vmcnt(" #n ")" ::: "memory"); __builtin_amdgcn_s_barrier(); asm volatile("" ::: "memory"); } while (0)
; #define RESC(a) do { if (__any((a) < 1.f)) { if (hi == 0) al_l[r32] = (a); asm volatile("s_waitcnt lgkmcnt(0)" ::: "memory"); \
;     for (int d = 0; d < 4; ++d) for (int r = 0; r < 16; ++r) o[d][r] *= al_l[crow(r, hi)]; } } while (0)
; __device__ __forceinline__ void attn_unit(const bf16* __restrict__ Qb, const bf16* __restrict__ Kh, const bf16* __restrict__ Vh, int klat0, int nlt, int kctx0, int NT,
;                                           float lam, float post, const float* __restrict__ subw, bf16* __restrict__ Ob, char* lds) {
;     ...
;       if (j + 2 < NT) TILE_BAR(4); else TILE_BAR(0);
;       if (j + 3 < NT) DMA_TILE(j + 3);
;       SBAR(); qkt(pA0, pA1, KS(j + 1), qr, r32, hi, sb);
;       finishSM(pB0, pB1, alB, l_reg, pa0, pa1, pa2, pa3); SBAR();
;       pv_d0(o, VB(j), pa0, pa1, pa2, pa3); partialSM(pA0, pA1, m_reg, mnA, alA);
;       RESC(alA);
;       if (j + 3 < NT) TILE_BAR(4); else TILE_BAR(0);
.LBB0_780:
	s_mov_b64 s[0:1], -1
	s_and_b64 vcc, exec, s[10:11]
	s_cbranch_vccz .LBB0_782
	s_waitcnt vmcnt(0)
	s_barrier
	v_readfirstlane_b32 s44, v0
	s_cmpk_lt_u32 s44, 0x100
	s_cbranch_scc1 .Lmy_ns2
	s_sleep 1

; #define SBAR() __builtin_amdgcn_sched_barrier(0)
; #define TILE_BAR(n) do { asm volatile("s_waitcnt vmcnt(" #n ")" ::: "memory"); __builtin_amdgcn_s_barrier(); asm volatile("" ::: "memory"); } while (0)
; #define RESC(a) do { if (__any((a) < 1.f)) { if (hi == 0) al_l[r32] = (a); asm volatile("s_waitcnt lgkmcnt(0)" ::: "memory"); \
;     for (int d = 0; d < 4; ++d) for (int r = 0; r < 16; ++r) o[d][r] *= al_l[crow(r, hi)]; } } while (0)
; __device__ __forceinline__ void finishSM(f32x16& p0, f32x16& p1, float alpha, float& l_reg, bf16x8& pa0, bf16x8& pa1, bf16x8& pa2, bf16x8& pa3) {
;     ...
;   l_reg = l_reg * alpha + ps;
; __device__ __forceinline__ void attn_unit(const bf16* __restrict__ Qb, const bf16* __restrict__ Kh, const bf16* __restrict__ Vh, int klat0, int nlt, int kctx0, int NT,
;                                           float lam, float post, const float* __restrict__ subw, bf16* __restrict__ Ob, char* lds) {
;     ...
;       if (j + 2 < NT) TILE_BAR(4); else TILE_BAR(0);
;       if (j + 3 < NT) DMA_TILE(j + 3);
;       SBAR(); qkt(pA0, pA1, KS(j + 1), qr, r32, hi, sb);
;       finishSM(pB0, pB1, alB, l_reg, pa0, pa1, pa2, pa3); SBAR();
;       pv_d0(o, VB(j), pa0, pa1, pa2, pa3); partialSM(pA0, pA1, m_reg, mnA, alA);
;       RESC(alA);
;       if (j + 3 < NT) TILE_BAR(4); else TILE_BAR(0);
;     }
.LBB0_782:
	s_andn2_b64 vcc, exec, s[0:1]
	s_cbranch_vccnz .LBB0_784
	s_waitcnt vmcnt(4)
	s_barrier
	v_readfirstlane_b32 s44, v0
	s_cmpk_lt_u32 s44, 0x100
	s_cbranch_scc1 .Lmy_ns3
	s_sleep 1
.Lmy_ns3:
.LBB0_784:
	v_add_f32_e32 v82, v130, v131
	v_fmac_f32_e32 v82, v173, v163
	v_add_f32_e32 v163, v99, v100
	v_fmac_f32_e32 v163, v82, v132
	s_add_i32 s36, s36, 0x8000
	s_and_b64 vcc, exec, s[10:11]
	s_cbranch_vccnz .LBB0_786
	s_mov_b32 s12, s37
	v_mov_b32_e32 v173, v205
	s_branch .LBB0_770
